# GLA p2 layer0 second-direction loop: next chunk q/k/v prefetched one chunk ahead
# baseline (speedup 1.0000x reference)
.LBB0_678:
	s_or_b64 exec, exec, s[54:55]
	s_lshl_b32 s48, s90, 2
	v_lshl_add_u64 v[134:135], v[132:133], 0, s[48:49]
	v_readlane_b32 s48, v240, 23
	s_add_u32 s48, s48, s68
	v_readlane_b32 s54, v240, 25
	s_addc_u32 s55, s54, 0
	s_add_i32 s54, s56, 0x140
	s_add_u32 s48, s48, s58
	s_addc_u32 s55, s55, s59
	s_add_u32 s56, s48, 0xe0000
	s_addc_u32 s57, s55, 0
	s_add_u32 s48, s73, s58
	s_addc_u32 s55, s86, s59
	s_add_u32 s58, s48, 0xe0000
	s_addc_u32 s59, s55, 0
	s_add_u32 s48, s53, s88
	s_addc_u32 s70, s51, s87
	s_add_u32 s55, s67, s88
	s_addc_u32 s60, s72, s87
	s_add_u32 s71, s55, 0x2a0000
	s_addc_u32 s74, s60, 0
	s_mov_b32 s75, 0
	s_mov_b64 s[60:61], 0
	s_waitcnt lgkmcnt(0)
	s_barrier
	s_add_u32 s62, s71, s60
	s_addc_u32 s63, s74, s61
	s_add_u32 s72, s48, s60
	s_addc_u32 s73, s70, s61
	s_add_u32 s55, s72, s68
	v_lshl_add_u64 v[232:233], s[62:63], 0, v[112:113]
	s_addc_u32 s63, s73, 0
	s_add_u32 s62, s55, 0xafc0800
	v_add_co_u32_e32 v244, vcc, s95, v232
	s_addc_u32 s63, s63, 0
	s_nop 0
	v_addc_co_u32_e32 v245, vcc, 0, v233, vcc
	v_lshl_add_u64 v[170:171], s[62:63], 0, v[114:115]
	v_add_co_u32_e32 v248, vcc, s81, v170
	s_nop 0
	v_addc_co_u32_e32 v249, vcc, 0, v171, vcc
	v_add_co_u32_e32 v252, vcc, s95, v170
	s_nop 0
	v_addc_co_u32_e32 v253, vcc, 0, v171, vcc
	global_load_dwordx4 v[192:195], v[232:233], off
	global_load_dwordx4 v[196:199], v[232:233], off offset:1024
	s_nop 0
	global_load_dwordx4 v[232:235], v[244:245], off
	global_load_dwordx4 v[236:239], v[244:245], off offset:1024
	global_load_dwordx4 v[244:247], v[170:171], off
	v_add_co_u32_e32 v170, vcc, s96, v170
	s_nop 0
	v_addc_co_u32_e32 v171, vcc, 0, v171, vcc
	global_load_dwordx4 v[248:251], v[248:249], off
	s_nop 0
	global_load_dwordx4 v[252:255], v[252:253], off
	s_nop 0
	global_load_dwordx4 v[170:173], v[170:171], off
	s_branch .LBB0_680

.LBB0_680:
	s_add_u32 s72, s48, s60
	s_addc_u32 s73, s70, s61
	s_and_b32 s67, s75, 1
	s_cmp_eq_u32 s67, 0
	s_cselect_b64 s[64:65], -1, 0
	s_and_b64 s[62:63], s[64:65], exec
	s_cselect_b32 s55, 0xf0, s69
	v_add3_u32 v105, s55, v177, v175
	ds_read2_b32 v[102:103], v105 offset1:4
	ds_read2_b32 v[136:137], v105 offset0:8 offset1:12
	s_waitcnt vmcnt(12) lgkmcnt(1)
	v_mfma_f32_16x16x4_f32 v[106:109], v102, v219, 0
	ds_read2_b32 v[140:141], v105 offset0:128 offset1:132
	s_waitcnt vmcnt(11)
	v_mfma_f32_16x16x4_f32 v[106:109], v103, v220, v[106:109]
	s_waitcnt vmcnt(10) lgkmcnt(1)
	v_mfma_f32_16x16x4_f32 v[106:109], v136, v221, v[106:109]
	s_waitcnt vmcnt(9)
	v_mfma_f32_16x16x4_f32 v[106:109], v137, v222, v[106:109]
	ds_read2_b32 v[136:137], v105 offset0:64 offset1:68
	s_waitcnt vmcnt(8)
	s_nop 7
	v_add_f32_e32 v102, v223, v106
	v_min_f32_e32 v0, 0, v102
	v_mul_f32_e64 v102, |v102|, s97
	v_exp_f32_e32 v102, v102
	v_add_f32_e32 v103, v223, v107
	v_add_f32_e32 v104, v223, v108
	v_add_f32_e32 v106, v223, v109
	v_add_f32_e32 v102, 1.0, v102
	v_log_f32_e32 v102, v102
	s_nop 0
	v_fmac_f32_e32 v0, 0xbf317218, v102
	v_min_f32_e32 v102, 0, v103
	v_mul_f32_e64 v103, |v103|, s97
	v_exp_f32_e32 v103, v103
	s_nop 0
	v_add_f32_e32 v103, 1.0, v103
	v_log_f32_e32 v103, v103
	s_nop 0
	v_fmac_f32_e32 v102, 0xbf317218, v103
	v_min_f32_e32 v103, 0, v104
	v_mul_f32_e64 v104, |v104|, s97
	v_exp_f32_e32 v104, v104
	s_nop 0
	v_add_f32_e32 v104, 1.0, v104
	v_log_f32_e32 v104, v104
	s_nop 0
	v_fmac_f32_e32 v103, 0xbf317218, v104
	v_min_f32_e32 v104, 0, v106
	v_mul_f32_e64 v106, |v106|, s97
	v_exp_f32_e32 v106, v106
	s_nop 0
	v_add_f32_e32 v106, 1.0, v106
	v_log_f32_e32 v106, v106
	s_nop 0
	v_fmac_f32_e32 v104, 0xbf317218, v106
	s_waitcnt lgkmcnt(0)
	v_mfma_f32_16x16x4_f32 v[106:109], v136, v219, 0
	v_mfma_f32_16x16x4_f32 v[106:109], v137, v220, v[106:109]
	ds_read2_b32 v[136:137], v105 offset0:72 offset1:76
	s_waitcnt lgkmcnt(0)
	v_mfma_f32_16x16x4_f32 v[106:109], v136, v221, v[106:109]
	v_mfma_f32_16x16x4_f32 v[106:109], v137, v222, v[106:109]
	s_nop 9
	v_add_f32_e32 v136, v223, v106
	v_min_f32_e32 v106, 0, v136
	v_mul_f32_e64 v136, |v136|, s97
	v_exp_f32_e32 v136, v136
	s_nop 0
	v_add_f32_e32 v136, 1.0, v136
	v_log_f32_e32 v136, v136
	s_nop 0
	v_fmac_f32_e32 v106, 0xbf317218, v136
	v_add_f32_e32 v136, v223, v107
	v_min_f32_e32 v107, 0, v136
	v_mul_f32_e64 v136, |v136|, s97
	v_exp_f32_e32 v136, v136
	s_nop 0
	v_add_f32_e32 v136, 1.0, v136
	v_log_f32_e32 v136, v136
	s_nop 0
	v_fmac_f32_e32 v107, 0xbf317218, v136
	v_add_f32_e32 v136, v223, v108
	v_min_f32_e32 v108, 0, v136
	v_mul_f32_e64 v136, |v136|, s97
	v_exp_f32_e32 v136, v136
	s_nop 0
	v_add_f32_e32 v136, 1.0, v136
	v_log_f32_e32 v136, v136
	s_nop 0
	v_fmac_f32_e32 v108, 0xbf317218, v136
	v_add_f32_e32 v136, v223, v109
	v_min_f32_e32 v109, 0, v136
	v_mul_f32_e64 v136, |v136|, s97
	v_exp_f32_e32 v136, v136
	s_nop 0
	v_add_f32_e32 v136, 1.0, v136
	v_log_f32_e32 v136, v136
	s_nop 0
	v_fmac_f32_e32 v109, 0xbf317218, v136
	v_mfma_f32_16x16x4_f32 v[136:139], v140, v219, 0
	v_mfma_f32_16x16x4_f32 v[136:139], v141, v220, v[136:139]
	ds_read2_b32 v[140:141], v105 offset0:136 offset1:140
	s_waitcnt lgkmcnt(0)
	v_mfma_f32_16x16x4_f32 v[136:139], v140, v221, v[136:139]
	v_mfma_f32_16x16x4_f32 v[136:139], v141, v222, v[136:139]
	ds_read2_b32 v[140:141], v105 offset0:192 offset1:196
	s_nop 8
	v_add_f32_e32 v136, v223, v136
	v_min_f32_e32 v142, 0, v136
	v_mul_f32_e64 v136, |v136|, s97
	v_exp_f32_e32 v136, v136
	s_nop 0
	v_add_f32_e32 v136, 1.0, v136
	v_log_f32_e32 v136, v136
	s_nop 0
	v_fmac_f32_e32 v142, 0xbf317218, v136
	v_add_f32_e32 v136, v223, v137
	v_min_f32_e32 v143, 0, v136
	v_mul_f32_e64 v136, |v136|, s97
	v_exp_f32_e32 v136, v136
	s_nop 0
	v_add_f32_e32 v136, 1.0, v136
	v_log_f32_e32 v136, v136
	s_nop 0
	v_fmac_f32_e32 v143, 0xbf317218, v136
	v_add_f32_e32 v136, v223, v138
	v_min_f32_e32 v144, 0, v136
	v_mul_f32_e64 v136, |v136|, s97
	v_exp_f32_e32 v136, v136
	s_nop 0
	v_add_f32_e32 v136, 1.0, v136
	v_log_f32_e32 v136, v136
	s_nop 0
	v_fmac_f32_e32 v144, 0xbf317218, v136
	v_add_f32_e32 v136, v223, v139
	v_min_f32_e32 v145, 0, v136
	v_mul_f32_e64 v136, |v136|, s97
	v_exp_f32_e32 v136, v136
	s_nop 0
	v_add_f32_e32 v136, 1.0, v136
	v_log_f32_e32 v136, v136
	s_nop 0
	v_fmac_f32_e32 v145, 0xbf317218, v136
	s_waitcnt lgkmcnt(0)
	v_mfma_f32_16x16x4_f32 v[136:139], v140, v219, 0
	v_mfma_f32_16x16x4_f32 v[136:139], v141, v220, v[136:139]
	ds_read2_b32 v[140:141], v105 offset0:200 offset1:204
	s_waitcnt lgkmcnt(0)
	v_mfma_f32_16x16x4_f32 v[136:139], v140, v221, v[136:139]
	v_mfma_f32_16x16x4_f32 v[136:139], v141, v222, v[136:139]
	s_nop 9
	v_add_f32_e32 v105, v223, v136
	v_min_f32_e32 v136, 0, v105
	v_mul_f32_e64 v105, |v105|, s97
	v_exp_f32_e32 v105, v105
	s_nop 0
	v_add_f32_e32 v105, 1.0, v105
	v_log_f32_e32 v105, v105
	s_nop 0
	v_fmac_f32_e32 v136, 0xbf317218, v105
	v_add_f32_e32 v105, v223, v137
	v_min_f32_e32 v137, 0, v105
	v_mul_f32_e64 v105, |v105|, s97
	v_exp_f32_e32 v105, v105
	s_nop 0
	v_add_f32_e32 v105, 1.0, v105
	v_log_f32_e32 v105, v105
	s_nop 0
	v_fmac_f32_e32 v137, 0xbf317218, v105
	v_add_f32_e32 v105, v223, v138
	v_min_f32_e32 v138, 0, v105
	v_mul_f32_e64 v105, |v105|, s97
	v_exp_f32_e32 v105, v105
	s_nop 0
	v_add_f32_e32 v105, 1.0, v105
	v_log_f32_e32 v105, v105
	s_nop 0
	v_fmac_f32_e32 v138, 0xbf317218, v105
	v_add_f32_e32 v105, v223, v139
	v_min_f32_e32 v139, 0, v105
	v_mul_f32_e64 v105, |v105|, s97
	v_exp_f32_e32 v105, v105
	s_nop 0
	v_add_f32_e32 v105, 1.0, v105
	v_log_f32_e32 v105, v105
	s_nop 0
	v_fmac_f32_e32 v139, 0xbf317218, v105
	v_fma_f32 v105, v139, s0, 0
	v_fmamk_f32 v138, v138, 0x3d800000, v105
	v_fmamk_f32 v137, v137, 0x3d800000, v138
	v_fmamk_f32 v136, v136, 0x3d800000, v137
	v_fmamk_f32 v139, v145, 0x3d800000, v136
	v_fmamk_f32 v140, v144, 0x3d800000, v139
	v_fmamk_f32 v141, v143, 0x3d800000, v140
	v_fmamk_f32 v142, v142, 0x3d800000, v141
	v_fmamk_f32 v109, v109, 0x3d800000, v142
	v_fmamk_f32 v108, v108, 0x3d800000, v109
	v_fmamk_f32 v107, v107, 0x3d800000, v108
	v_fmamk_f32 v106, v106, 0x3d800000, v107
	v_fmamk_f32 v104, v104, 0x3d800000, v106
	v_fmamk_f32 v103, v103, 0x3d800000, v104
	v_fmamk_f32 v102, v102, 0x3d800000, v103
	v_fmamk_f32 v0, v0, 0x3d800000, v102
	ds_bpermute_b32 v144, v188, v0
	ds_bpermute_b32 v145, v189, v0
	ds_bpermute_b32 v143, v187, v0
	s_waitcnt lgkmcnt(2)
	v_cndmask_b32_e64 v144, 0, v144, s[28:29]
	s_waitcnt lgkmcnt(1)
	v_cndmask_b32_e64 v145, v145, 0, s[8:9]
	v_add_f32_e32 v144, v144, v145
	s_waitcnt lgkmcnt(0)
	v_cndmask_b32_e64 v143, 0, v143, s[4:5]
	v_add_f32_e32 v143, v143, v144
	v_add_f32_e32 v0, v143, v0
	v_add_f32_e32 v102, v143, v102
	ds_write2st64_b32 v200, v0, v102 offset0:24 offset1:26
	v_add_f32_e32 v0, v143, v103
	v_add_f32_e32 v102, v143, v104
	ds_write2st64_b32 v200, v0, v102 offset0:28 offset1:30
	v_add_f32_e32 v0, v143, v106
	v_add_f32_e32 v102, v143, v107
	ds_write2st64_b32 v200, v0, v102 offset0:32 offset1:34
	v_add_f32_e32 v0, v143, v108
	v_add_f32_e32 v102, v143, v109
	ds_write2st64_b32 v200, v0, v102 offset0:36 offset1:38
	v_add_f32_e32 v0, v143, v142
	v_add_f32_e32 v102, v143, v141
	ds_write2st64_b32 v200, v0, v102 offset0:40 offset1:42
	v_add_f32_e32 v0, v143, v140
	v_add_f32_e32 v102, v143, v139
	ds_write2st64_b32 v200, v0, v102 offset0:44 offset1:46
	v_add_f32_e32 v0, v143, v136
	v_add_f32_e32 v102, v143, v137
	ds_write2st64_b32 v200, v0, v102 offset0:48 offset1:50
	v_add_f32_e32 v0, v143, v138
	v_add_f32_e32 v102, v143, v105
	ds_write2st64_b32 v200, v0, v102 offset0:52 offset1:54
	s_waitcnt lgkmcnt(0)
	s_barrier
	s_and_saveexec_b64 s[62:63], s[10:11]
	s_cbranch_execz .LBB0_682
	ds_read_b32 v0, v178 offset:6144
	v_lshl_add_u32 v102, s67, 9, v178
	s_waitcnt lgkmcnt(0)
	ds_write_b32 v102, v0 offset:4096

.LBB0_689:
	ds_read_b128 v[102:105], v201 offset:6144
	ds_read_b128 v[106:109], v201 offset:6160
	s_waitcnt vmcnt(6)
	v_lshlrev_b32_e32 v138, 16, v196
	v_and_b32_e32 v139, 0xffff0000, v196
	s_waitcnt lgkmcnt(1)
	v_mul_f32_e32 v0, 0xbfb8aa3b, v102
	v_exp_f32_e32 v136, v0
	v_mul_f32_e32 v0, 0xbfb8aa3b, v103
	v_exp_f32_e32 v137, v0
	v_mul_f32_e32 v0, 0xbfb8aa3b, v104
	v_pk_mul_f32 v[136:137], v[136:137], v[138:139]
	s_nop 0
	v_cvt_pk_bf16_f32 v98, v136, v137
	v_exp_f32_e32 v136, v0
	v_mul_f32_e32 v0, 0xbfb8aa3b, v105
	v_exp_f32_e32 v137, v0
	v_lshlrev_b32_e32 v138, 16, v197
	v_and_b32_e32 v139, 0xffff0000, v197
	s_waitcnt lgkmcnt(0)
	v_mul_f32_e32 v0, 0xbfb8aa3b, v106
	v_pk_mul_f32 v[136:137], v[136:137], v[138:139]
	v_lshlrev_b32_e32 v138, 16, v198
	v_cvt_pk_bf16_f32 v99, v136, v137
	v_exp_f32_e32 v136, v0
	v_mul_f32_e32 v0, 0xbfb8aa3b, v107
	v_exp_f32_e32 v137, v0
	v_and_b32_e32 v139, 0xffff0000, v198
	v_mul_f32_e32 v0, 0xbfb8aa3b, v108
	v_pk_mul_f32 v[136:137], v[136:137], v[138:139]
	s_nop 0
	v_cvt_pk_bf16_f32 v100, v136, v137
	v_exp_f32_e32 v136, v0
	v_mul_f32_e32 v0, 0xbfb8aa3b, v109
	v_exp_f32_e32 v137, v0
	v_lshlrev_b32_e32 v138, 16, v199
	v_and_b32_e32 v139, 0xffff0000, v199
	v_mul_f32_e32 v0, 0x3fb8aa3b, v102
	v_pk_mul_f32 v[136:137], v[136:137], v[138:139]
	s_nop 0
	v_cvt_pk_bf16_f32 v101, v136, v137
	ds_write_b128 v181, v[98:101] offset:56320
	v_exp_f32_e32 v98, v0
	v_mul_f32_e32 v0, 0x3fb8aa3b, v103
	v_exp_f32_e32 v99, v0
	v_lshlrev_b32_e32 v100, 16, v192
	v_and_b32_e32 v101, 0xffff0000, v192
	v_mul_f32_e32 v0, 0x3fb8aa3b, v104
	v_pk_mul_f32 v[98:99], v[98:99], s[50:51] op_sel_hi:[1,0]
	s_waitcnt vmcnt(4)
	v_lshlrev_b32_e32 v104, 16, v236
	v_pk_mul_f32 v[98:99], v[98:99], v[100:101]
	v_lshlrev_b32_e32 v100, 16, v193
	v_cvt_pk_bf16_f32 v94, v98, v99
	v_exp_f32_e32 v98, v0
	v_mul_f32_e32 v0, 0x3fb8aa3b, v105
	v_exp_f32_e32 v99, v0
	v_and_b32_e32 v101, 0xffff0000, v193
	v_mul_f32_e32 v0, 0x3fb8aa3b, v106
	v_and_b32_e32 v105, 0xffff0000, v236
	v_pk_mul_f32 v[98:99], v[98:99], s[50:51] op_sel_hi:[1,0]
	s_nop 0
	v_pk_mul_f32 v[98:99], v[98:99], v[100:101]
	v_lshlrev_b32_e32 v100, 16, v194
	v_cvt_pk_bf16_f32 v95, v98, v99
	v_exp_f32_e32 v98, v0
	v_mul_f32_e32 v0, 0x3fb8aa3b, v107
	v_exp_f32_e32 v99, v0
	v_and_b32_e32 v101, 0xffff0000, v194
	v_mul_f32_e32 v0, 0x3fb8aa3b, v108
	v_pk_mul_f32 v[98:99], v[98:99], s[50:51] op_sel_hi:[1,0]
	s_nop 0
	v_pk_mul_f32 v[98:99], v[98:99], v[100:101]
	v_lshlrev_b32_e32 v100, 16, v195
	v_cvt_pk_bf16_f32 v96, v98, v99
	v_exp_f32_e32 v98, v0
	v_mul_f32_e32 v0, 0x3fb8aa3b, v109
	v_exp_f32_e32 v99, v0
	v_and_b32_e32 v101, 0xffff0000, v195
	v_pk_mul_f32 v[98:99], v[98:99], s[50:51] op_sel_hi:[1,0]
	s_nop 0
	v_pk_mul_f32 v[98:99], v[98:99], v[100:101]
	s_nop 0
	v_cvt_pk_bf16_f32 v97, v98, v99
	ds_write_b128 v181, v[94:97] offset:38912
	ds_read_b128 v[94:97], v202 offset:6144
	ds_read_b128 v[98:101], v202 offset:6160
	s_waitcnt lgkmcnt(1)
	v_mul_f32_e32 v0, 0xbfb8aa3b, v94
	v_exp_f32_e32 v102, v0
	v_mul_f32_e32 v0, 0xbfb8aa3b, v95
	v_exp_f32_e32 v103, v0
	v_mul_f32_e32 v0, 0xbfb8aa3b, v96
	v_pk_mul_f32 v[102:103], v[102:103], v[104:105]
	s_nop 0
	v_cvt_pk_bf16_f32 v90, v102, v103
	v_exp_f32_e32 v102, v0
	v_mul_f32_e32 v0, 0xbfb8aa3b, v97
	v_exp_f32_e32 v103, v0
	v_lshlrev_b32_e32 v104, 16, v237
	v_and_b32_e32 v105, 0xffff0000, v237
	s_waitcnt lgkmcnt(0)
	v_mul_f32_e32 v0, 0xbfb8aa3b, v98
	v_pk_mul_f32 v[102:103], v[102:103], v[104:105]
	v_lshlrev_b32_e32 v104, 16, v238
	v_cvt_pk_bf16_f32 v91, v102, v103
	v_exp_f32_e32 v102, v0
	v_mul_f32_e32 v0, 0xbfb8aa3b, v99
	v_exp_f32_e32 v103, v0
	v_and_b32_e32 v105, 0xffff0000, v238
	v_mul_f32_e32 v0, 0xbfb8aa3b, v100
	v_pk_mul_f32 v[102:103], v[102:103], v[104:105]
	s_nop 0
	v_cvt_pk_bf16_f32 v92, v102, v103
	v_exp_f32_e32 v102, v0
	v_mul_f32_e32 v0, 0xbfb8aa3b, v101
	v_exp_f32_e32 v103, v0
	v_lshlrev_b32_e32 v104, 16, v239
	v_and_b32_e32 v105, 0xffff0000, v239
	v_mul_f32_e32 v0, 0x3fb8aa3b, v94
	v_pk_mul_f32 v[102:103], v[102:103], v[104:105]
	s_nop 0
	v_cvt_pk_bf16_f32 v93, v102, v103
	ds_write_b128 v182, v[90:93] offset:56320
	v_exp_f32_e32 v90, v0
	v_mul_f32_e32 v0, 0x3fb8aa3b, v95
	v_exp_f32_e32 v91, v0
	v_lshlrev_b32_e32 v92, 16, v232
	v_and_b32_e32 v93, 0xffff0000, v232
	v_mul_f32_e32 v0, 0x3fb8aa3b, v96
	v_pk_mul_f32 v[90:91], v[90:91], s[50:51] op_sel_hi:[1,0]
	s_nop 0
	v_pk_mul_f32 v[90:91], v[90:91], v[92:93]
	v_lshlrev_b32_e32 v92, 16, v233
	v_cvt_pk_bf16_f32 v70, v90, v91
	v_exp_f32_e32 v90, v0
	v_mul_f32_e32 v0, 0x3fb8aa3b, v97
	v_exp_f32_e32 v91, v0
	v_and_b32_e32 v93, 0xffff0000, v233
	v_mul_f32_e32 v0, 0x3fb8aa3b, v98
	v_pk_mul_f32 v[90:91], v[90:91], s[50:51] op_sel_hi:[1,0]
	s_nop 0
	v_pk_mul_f32 v[90:91], v[90:91], v[92:93]
	v_lshlrev_b32_e32 v92, 16, v234
	v_cvt_pk_bf16_f32 v71, v90, v91
	v_exp_f32_e32 v90, v0
	v_mul_f32_e32 v0, 0x3fb8aa3b, v99
	v_exp_f32_e32 v91, v0
	v_and_b32_e32 v93, 0xffff0000, v234
	v_mul_f32_e32 v0, 0x3fb8aa3b, v100
	v_pk_mul_f32 v[90:91], v[90:91], s[50:51] op_sel_hi:[1,0]
	s_nop 0
	v_pk_mul_f32 v[90:91], v[90:91], v[92:93]
	v_lshlrev_b32_e32 v92, 16, v235
	v_cvt_pk_bf16_f32 v72, v90, v91
	v_exp_f32_e32 v90, v0
	v_mul_f32_e32 v0, 0x3fb8aa3b, v101
	v_exp_f32_e32 v91, v0
	v_and_b32_e32 v93, 0xffff0000, v235
	v_pk_mul_f32 v[90:91], v[90:91], s[50:51] op_sel_hi:[1,0]
	s_nop 0
	v_pk_mul_f32 v[90:91], v[90:91], v[92:93]
	s_nop 0
	v_cvt_pk_bf16_f32 v73, v90, v91
	ds_write_b128 v182, v[70:73] offset:38912
	s_waitcnt vmcnt(3)
	ds_write_b128 v203, v[244:247]
	s_waitcnt vmcnt(2)
	ds_write_b128 v204, v[248:251]
	s_waitcnt vmcnt(1)
	ds_write_b128 v203, v[252:255] offset:16896
	s_waitcnt vmcnt(0)
	ds_write_b128 v205, v[170:173]
	v_lshl_add_u64 v[70:71], s[58:59], 0, v[116:117]
	v_lshl_add_u64 v[72:73], s[58:59], 0, v[120:121]
	v_lshl_add_u64 v[74:75], s[58:59], 0, v[122:123]
	global_load_dwordx2 v[156:157], v[70:71], off
	global_load_dwordx2 v[152:153], v[70:71], off offset:32
	global_load_dwordx2 v[148:149], v[72:73], off
	global_load_dwordx2 v[146:147], v[74:75], off
	v_lshl_add_u64 v[70:71], s[58:59], 0, v[124:125]
	v_lshl_add_u64 v[72:73], s[58:59], 0, v[126:127]
	v_lshl_add_u64 v[74:75], s[58:59], 0, v[128:129]
	v_lshl_add_u64 v[76:77], s[58:59], 0, v[130:131]
	global_load_dwordx2 v[144:145], v[70:71], off
	global_load_dwordx2 v[142:143], v[72:73], off
	global_load_dwordx2 v[138:139], v[74:75], off
	global_load_dwordx2 v[136:137], v[76:77], off
	s_cmp_lt_u32 s75, 7
	s_cselect_b32 s98, 0xfffa0000, 0
	s_cselect_b32 s99, -1, 0
	s_add_u32 s98, s98, s60
	s_addc_u32 s99, s99, s61
	s_add_u32 s62, s71, s98
	s_addc_u32 s63, s74, s99
	s_add_u32 s100, s48, s98
	s_addc_u32 s101, s70, s99
	s_add_u32 s55, s100, s68
	v_lshl_add_u64 v[232:233], s[62:63], 0, v[112:113]
	s_addc_u32 s63, s101, 0
	s_add_u32 s62, s55, 0xafc0800
	v_add_co_u32_e32 v244, vcc, s95, v232
	s_addc_u32 s63, s63, 0
	s_nop 0
	v_addc_co_u32_e32 v245, vcc, 0, v233, vcc
	v_lshl_add_u64 v[170:171], s[62:63], 0, v[114:115]
	v_add_co_u32_e32 v248, vcc, s81, v170
	s_nop 0
	v_addc_co_u32_e32 v249, vcc, 0, v171, vcc
	v_add_co_u32_e32 v252, vcc, s95, v170
	s_nop 0
	v_addc_co_u32_e32 v253, vcc, 0, v171, vcc
	global_load_dwordx4 v[192:195], v[232:233], off
	global_load_dwordx4 v[196:199], v[232:233], off offset:1024
	s_nop 0
	global_load_dwordx4 v[232:235], v[244:245], off
	global_load_dwordx4 v[236:239], v[244:245], off offset:1024
	global_load_dwordx4 v[244:247], v[170:171], off
	v_add_co_u32_e32 v170, vcc, s96, v170
	s_nop 0
	v_addc_co_u32_e32 v171, vcc, 0, v171, vcc
	global_load_dwordx4 v[248:251], v[248:249], off
	s_nop 0
	global_load_dwordx4 v[252:255], v[252:253], off
	s_nop 0
	global_load_dwordx4 v[170:173], v[170:171], off
	s_waitcnt lgkmcnt(0)
	s_barrier
	ds_read_b128 v[70:73], v206 offset:56320
	ds_read_b128 v[74:77], v180 offset:38912
	ds_read_b128 v[78:81], v206 offset:56384
	ds_read_b128 v[82:85], v180 offset:38976
	s_waitcnt lgkmcnt(2)
	v_mfma_f32_16x16x32_bf16 v[70:73], v[70:73], v[74:77], 0
	v_mov_b32_e32 v0, s49
	v_cvt_pk_bf16_f32 v166, v62, v63
	v_cvt_pk_bf16_f32 v167, v64, v65
	s_waitcnt lgkmcnt(0)
	v_mfma_f32_16x16x32_bf16 v[70:73], v[78:81], v[82:85], v[70:73]
	ds_read_b128 v[78:81], v206 offset:56448
	ds_read_b128 v[86:89], v180 offset:39040
	v_cvt_pk_bf16_f32 v168, v66, v67
	v_cvt_pk_bf16_f32 v169, v68, v69
	s_waitcnt lgkmcnt(0)
	v_mfma_f32_16x16x32_bf16 v[70:73], v[78:81], v[86:89], v[70:73]
	ds_read_b128 v[78:81], v206 offset:56512
	ds_read_b128 v[90:93], v180 offset:39104
	s_add_u32 s55, s72, s68
	s_addc_u32 s63, s73, 0
	s_waitcnt lgkmcnt(0)
	v_mfma_f32_16x16x32_bf16 v[70:73], v[78:81], v[90:93], v[70:73]
	s_add_u32 s62, s55, 0xafc1000
	s_addc_u32 s63, s63, 0
	s_waitcnt vmcnt(15)
	v_lshlrev_b32_e32 v224, 16, v156
	s_nop 3
	v_cndmask_b32_e64 v0, v70, v0, s[14:15]
	v_cndmask_b32_e64 v70, v71, 0, s[30:31]
	v_cndmask_b32_e64 v71, v72, 0, s[34:35]
	v_cndmask_b32_e64 v72, v73, 0, s[36:37]
	v_cvt_pk_bf16_f32 v70, v0, v70
	v_cvt_pk_bf16_f32 v71, v71, v72
	ds_write_b64 v207, v[70:71]
	ds_read_b128 v[70:73], v208 offset:56320
	s_waitcnt lgkmcnt(0)
	v_mfma_f32_16x16x32_bf16 v[70:73], v[70:73], v[74:77], 0
	ds_read_b128 v[74:77], v208 offset:56384
	v_mov_b32_e32 v0, s49
	v_and_b32_e32 v225, 0xffff0000, v156
	s_waitcnt lgkmcnt(0)
	v_mfma_f32_16x16x32_bf16 v[70:73], v[74:77], v[82:85], v[70:73]
	ds_read_b128 v[74:77], v208 offset:56448
	v_lshlrev_b32_e32 v156, 16, v157
	v_and_b32_e32 v157, 0xffff0000, v157
	s_waitcnt lgkmcnt(0)
	v_mfma_f32_16x16x32_bf16 v[70:73], v[74:77], v[86:89], v[70:73]
	ds_read_b128 v[74:77], v208 offset:56512
	s_waitcnt vmcnt(14)
	v_lshlrev_b32_e32 v226, 16, v152
	v_and_b32_e32 v227, 0xffff0000, v152
	s_waitcnt lgkmcnt(0)
	v_mfma_f32_16x16x32_bf16 v[70:73], v[74:77], v[90:93], v[70:73]
	v_lshlrev_b32_e32 v152, 16, v153
	v_and_b32_e32 v153, 0xffff0000, v153
	s_nop 5
	v_cndmask_b32_e64 v0, v70, v0, s[22:23]
	v_cndmask_b32_e64 v70, v71, 0, s[38:39]
	v_cndmask_b32_e64 v71, v72, 0, s[40:41]
	v_cndmask_b32_e64 v72, v73, 0, s[42:43]
	v_cvt_pk_bf16_f32 v70, v0, v70
	v_cvt_pk_bf16_f32 v71, v71, v72
	ds_write_b64 v209, v[70:71]
	s_waitcnt lgkmcnt(0)
	s_barrier
	ds_read_b64_tr_b16 v[72:73], v210 offset:2112
	ds_read_b64_tr_b16 v[70:71], v210
	ds_read_b64_tr_b16 v[74:75], v210 offset:32
	ds_read_b64_tr_b16 v[78:79], v210 offset:16896
	ds_read_b64_tr_b16 v[80:81], v210 offset:19008
	ds_read_b64_tr_b16 v[76:77], v210 offset:2144
	ds_read_b64_tr_b16 v[82:83], v210 offset:16928
	ds_read_b64_tr_b16 v[84:85], v210 offset:19040
	ds_read_b128 v[86:89], v211
	ds_read_b128 v[94:97], v211 offset:64
	ds_read_b128 v[102:105], v211 offset:2368
	s_waitcnt lgkmcnt(2)
	v_mfma_f32_16x16x32_bf16 v[90:93], v[70:73], v[86:89], 0
	ds_read_b128 v[158:161], v211 offset:4672
	v_mfma_f32_16x16x32_bf16 v[86:89], v[74:77], v[86:89], 0
	s_waitcnt lgkmcnt(2)
	v_mfma_f32_16x16x32_bf16 v[90:93], v[78:81], v[94:97], v[90:93]
	v_mfma_f32_16x16x32_bf16 v[86:89], v[82:85], v[94:97], v[86:89]
	ds_read_b128 v[94:97], v211 offset:2304
	s_waitcnt lgkmcnt(0)
	v_mfma_f32_16x16x32_bf16 v[98:101], v[70:73], v[94:97], 0
	v_mfma_f32_16x16x32_bf16 v[94:97], v[74:77], v[94:97], 0
	v_mfma_f32_16x16x32_bf16 v[98:101], v[78:81], v[102:105], v[98:101]
	v_mfma_f32_16x16x32_bf16 v[94:97], v[82:85], v[102:105], v[94:97]
	ds_read_b128 v[102:105], v211 offset:4608
	s_waitcnt lgkmcnt(0)
	v_mfma_f32_16x16x32_bf16 v[106:109], v[70:73], v[102:105], 0
	v_mfma_f32_16x16x32_bf16 v[102:105], v[74:77], v[102:105], 0
	v_mfma_f32_16x16x32_bf16 v[106:109], v[78:81], v[158:161], v[106:109]
	v_mfma_f32_16x16x32_bf16 v[102:105], v[82:85], v[158:161], v[102:105]
	ds_read_b128 v[158:161], v211 offset:6912
	s_waitcnt lgkmcnt(0)
	v_mfma_f32_16x16x32_bf16 v[70:73], v[70:73], v[158:161], 0
	v_mfma_f32_16x16x32_bf16 v[74:77], v[74:77], v[158:161], 0
	ds_read_b128 v[158:161], v211 offset:6976
	s_waitcnt lgkmcnt(0)
	v_mfma_f32_16x16x32_bf16 v[70:73], v[78:81], v[158:161], v[70:73]
	v_cvt_pk_bf16_f32 v78, v30, v31
	v_cvt_pk_bf16_f32 v79, v32, v33
	v_cvt_pk_bf16_f32 v80, v10, v11
	v_mfma_f32_16x16x32_bf16 v[74:77], v[82:85], v[158:161], v[74:77]
	v_cvt_pk_bf16_f32 v81, v12, v13
	v_cvt_pk_bf16_f32 v82, v6, v7
	v_cvt_pk_bf16_f32 v83, v8, v9
	v_cvt_pk_bf16_f32 v84, v18, v19
	v_cvt_pk_bf16_f32 v85, v20, v21
	ds_read2_b64 v[158:161], v215 offset1:4
	s_waitcnt lgkmcnt(0)
	v_mfma_f32_16x16x32_bf16 v[90:93], v[78:81], v[158:161], v[90:93]
	v_mfma_f32_16x16x32_bf16 v[86:89], v[82:85], v[158:161], v[86:89]
	ds_read2_b64 v[158:161], v216 offset0:32 offset1:36
	s_waitcnt lgkmcnt(0)
	v_mfma_f32_16x16x32_bf16 v[98:101], v[78:81], v[158:161], v[98:101]
	v_mfma_f32_16x16x32_bf16 v[94:97], v[82:85], v[158:161], v[94:97]
	ds_read2_b64 v[158:161], v217 offset0:64 offset1:68
	s_waitcnt lgkmcnt(0)
	v_mfma_f32_16x16x32_bf16 v[106:109], v[78:81], v[158:161], v[106:109]
	v_mfma_f32_16x16x32_bf16 v[102:105], v[82:85], v[158:161], v[102:105]
	ds_read2_b64 v[158:161], v218 offset0:96 offset1:100
	s_waitcnt lgkmcnt(0)
	v_mfma_f32_16x16x32_bf16 v[70:73], v[78:81], v[158:161], v[70:73]
	v_cvt_pk_bf16_f32 v78, v14, v15
	v_cvt_pk_bf16_f32 v79, v16, v17
	v_cvt_pk_bf16_f32 v80, v38, v39
	v_mfma_f32_16x16x32_bf16 v[74:77], v[82:85], v[158:161], v[74:77]
	v_cvt_pk_bf16_f32 v81, v40, v41
	v_cvt_pk_bf16_f32 v82, v26, v27
	v_cvt_pk_bf16_f32 v83, v28, v29
	v_cvt_pk_bf16_f32 v84, v50, v51
	v_cvt_pk_bf16_f32 v85, v52, v53
	ds_read2_b64 v[158:161], v215 offset0:8 offset1:12
	s_waitcnt lgkmcnt(0)
	v_mfma_f32_16x16x32_bf16 v[90:93], v[78:81], v[158:161], v[90:93]
	v_mfma_f32_16x16x32_bf16 v[86:89], v[82:85], v[158:161], v[86:89]
	ds_read2_b64 v[158:161], v216 offset0:40 offset1:44
	s_waitcnt lgkmcnt(0)
	v_mfma_f32_16x16x32_bf16 v[98:101], v[78:81], v[158:161], v[98:101]
	v_mfma_f32_16x16x32_bf16 v[94:97], v[82:85], v[158:161], v[94:97]
	ds_read2_b64 v[158:161], v217 offset0:72 offset1:76
	s_waitcnt lgkmcnt(0)
	v_mfma_f32_16x16x32_bf16 v[106:109], v[78:81], v[158:161], v[106:109]
	v_mfma_f32_16x16x32_bf16 v[102:105], v[82:85], v[158:161], v[102:105]
	ds_read2_b64 v[158:161], v218 offset0:104 offset1:108
	s_waitcnt lgkmcnt(0)
	v_mfma_f32_16x16x32_bf16 v[70:73], v[78:81], v[158:161], v[70:73]
	v_cvt_pk_bf16_f32 v78, v22, v23
	v_cvt_pk_bf16_f32 v79, v24, v25
	v_cvt_pk_bf16_f32 v80, v42, v43
	v_mfma_f32_16x16x32_bf16 v[74:77], v[82:85], v[158:161], v[74:77]
	v_cvt_pk_bf16_f32 v81, v44, v45
	v_cvt_pk_bf16_f32 v82, v34, v35
	v_cvt_pk_bf16_f32 v83, v36, v37
	v_cvt_pk_bf16_f32 v84, v54, v55
	v_cvt_pk_bf16_f32 v85, v56, v57
	ds_read2_b64 v[158:161], v215 offset0:16 offset1:20
	s_waitcnt lgkmcnt(0)
	v_mfma_f32_16x16x32_bf16 v[90:93], v[78:81], v[158:161], v[90:93]
	v_mfma_f32_16x16x32_bf16 v[86:89], v[82:85], v[158:161], v[86:89]
	ds_read2_b64 v[158:161], v216 offset0:48 offset1:52
	s_waitcnt lgkmcnt(0)
	v_mfma_f32_16x16x32_bf16 v[98:101], v[78:81], v[158:161], v[98:101]
	v_mfma_f32_16x16x32_bf16 v[94:97], v[82:85], v[158:161], v[94:97]
	ds_read2_b64 v[158:161], v217 offset0:80 offset1:84
	s_waitcnt lgkmcnt(0)
	v_mfma_f32_16x16x32_bf16 v[162:165], v[78:81], v[158:161], v[106:109]
	v_mfma_f32_16x16x32_bf16 v[158:161], v[82:85], v[158:161], v[102:105]
	s_nop 2
	ds_read2_b64 v[102:105], v218 offset0:112 offset1:116
	s_waitcnt lgkmcnt(0)
	v_mfma_f32_16x16x32_bf16 v[70:73], v[78:81], v[102:105], v[70:73]
	v_cvt_pk_bf16_f32 v78, v46, v47
	v_cvt_pk_bf16_f32 v79, v48, v49
	v_cvt_pk_bf16_f32 v80, v58, v59
	v_mfma_f32_16x16x32_bf16 v[74:77], v[82:85], v[102:105], v[74:77]
	v_cvt_pk_bf16_f32 v81, v60, v61
	ds_read2_b64 v[82:85], v215 offset0:24 offset1:28
	s_waitcnt lgkmcnt(0)
	v_mfma_f32_16x16x32_bf16 v[106:109], v[78:81], v[82:85], v[90:93]
	v_mfma_f32_16x16x32_bf16 v[102:105], v[166:169], v[82:85], v[86:89]
	ds_read2_b64 v[82:85], v216 offset0:56 offset1:60
	s_nop 5
	v_pk_add_f32 v[106:107], v[106:107], v[224:225]
	v_pk_add_f32 v[108:109], v[108:109], v[156:157]
	s_waitcnt lgkmcnt(0)
	v_mfma_f32_16x16x32_bf16 v[98:101], v[78:81], v[82:85], v[98:101]
	v_mul_f32_e64 v156, v106, v106
	v_mul_f32_e64 v157, v107, v107
	v_pk_mul_f32 v[224:225], v[108:109], v[108:109]
	v_add_f32_e32 v0, v156, v157
	v_mfma_f32_16x16x32_bf16 v[94:97], v[166:169], v[82:85], v[94:97]
	ds_read2_b64 v[82:85], v217 offset0:88 offset1:92
	v_pk_add_f32 v[102:103], v[102:103], v[226:227]
	v_add_f32_e32 v0, v224, v0
	s_waitcnt lgkmcnt(0)
	v_mfma_f32_16x16x32_bf16 v[86:89], v[166:169], v[82:85], v[158:161]
	v_add_f32_e64 v104, v104, v152
	v_add_f32_e64 v105, v105, v153
	s_nop 0
	ds_read2_b64 v[158:161], v218 offset0:120 offset1:124
	v_pk_mul_f32 v[152:153], v[102:103], v[102:103]
	v_mfma_f32_16x16x32_bf16 v[90:93], v[78:81], v[82:85], v[162:165]
	v_add_f32_e32 v0, v225, v0
	v_add_f32_e32 v0, v152, v0
	v_pk_mul_f32 v[226:227], v[104:105], v[104:105]
	s_waitcnt lgkmcnt(0)
	v_mfma_f32_16x16x32_bf16 v[82:85], v[78:81], v[158:161], v[70:73]
	v_add_f32_e32 v0, v153, v0
	v_add_f32_e32 v0, v226, v0
	v_add_f32_e32 v0, v227, v0
	v_lshl_add_u64 v[70:71], s[62:63], 0, v[118:119]
	v_add_co_u32_e32 v72, vcc, s81, v70
	v_mfma_f32_16x16x32_bf16 v[78:81], v[166:169], v[158:161], v[74:77]
	s_nop 0
	v_addc_co_u32_e32 v73, vcc, 0, v71, vcc
	global_load_dwordx2 v[168:169], v[70:71], off
	global_load_dwordx2 v[166:167], v[70:71], off offset:32
	global_load_dwordx2 v[164:165], v[72:73], off
	global_load_dwordx2 v[162:163], v[72:73], off offset:32
	v_add_co_u32_e32 v72, vcc, s95, v70
	ds_bpermute_b32 v152, v190, v0
	s_nop 0
	v_addc_co_u32_e32 v73, vcc, 0, v71, vcc
	v_add_co_u32_e32 v70, vcc, s96, v70
	global_load_dwordx2 v[160:161], v[72:73], off
	global_load_dwordx2 v[158:159], v[72:73], off offset:32
	v_addc_co_u32_e32 v71, vcc, 0, v71, vcc
	global_load_dwordx2 v[150:151], v[70:71], off
	global_load_dwordx2 v[140:141], v[70:71], off offset:32
	global_load_dwordx4 v[74:77], v[134:135], off
	s_nop 0
	global_load_dwordx4 v[70:73], v[134:135], off offset:64
	s_waitcnt lgkmcnt(0)
	v_add_f32_e32 v0, v0, v152
	ds_bpermute_b32 v152, v191, v0
	s_and_saveexec_b64 s[62:63], s[4:5]
	s_cbranch_execz .LBB0_691
	s_waitcnt lgkmcnt(0)
	v_add_f32_e32 v0, v0, v152
	ds_write_b32 v185, v0
.LBB0_691:
	s_or_b64 exec, exec, s[62:63]
	s_waitcnt vmcnt(23) lgkmcnt(0)
	v_lshlrev_b32_e32 v152, 16, v148
	v_and_b32_e32 v153, 0xffff0000, v148
	v_pk_add_f32 v[152:153], v[98:99], v[152:153]
	v_lshlrev_b32_e32 v98, 16, v149
	v_and_b32_e32 v99, 0xffff0000, v149
	v_pk_add_f32 v[100:101], v[100:101], v[98:99]
	v_pk_mul_f32 v[148:149], v[152:153], v[152:153]
	v_pk_mul_f32 v[156:157], v[100:101], v[100:101]
	s_waitcnt vmcnt(22)
	v_lshlrev_b32_e32 v98, 16, v146
	v_and_b32_e32 v99, 0xffff0000, v146
	v_add_f32_e32 v0, v148, v149
	v_pk_add_f32 v[98:99], v[94:95], v[98:99]
	v_lshlrev_b32_e32 v94, 16, v147
	v_and_b32_e32 v95, 0xffff0000, v147
	v_add_f32_e32 v0, v156, v0
	v_pk_add_f32 v[96:97], v[96:97], v[94:95]
	v_pk_mul_f32 v[94:95], v[98:99], v[98:99]
	v_add_f32_e32 v0, v157, v0
	v_add_f32_e32 v0, v94, v0
	v_pk_mul_f32 v[146:147], v[96:97], v[96:97]
	v_add_f32_e32 v0, v95, v0
	v_add_f32_e32 v0, v146, v0
	v_add_f32_e32 v0, v147, v0
	ds_bpermute_b32 v94, v190, v0
	s_waitcnt lgkmcnt(0)
	v_add_f32_e32 v0, v0, v94
	ds_bpermute_b32 v94, v191, v0
	s_and_saveexec_b64 s[62:63], s[4:5]
	s_cbranch_execz .LBB0_693
	s_waitcnt lgkmcnt(0)
	v_add_f32_e32 v0, v0, v94
	ds_write_b32 v185, v0 offset:512
.LBB0_693:
	s_or_b64 exec, exec, s[62:63]
	s_waitcnt vmcnt(21) lgkmcnt(0)
	v_lshlrev_b32_e32 v94, 16, v144
	v_and_b32_e32 v95, 0xffff0000, v144
	v_pk_add_f32 v[90:91], v[90:91], v[94:95]
	v_lshlrev_b32_e32 v94, 16, v145
	v_and_b32_e32 v95, 0xffff0000, v145
	v_pk_add_f32 v[94:95], v[92:93], v[94:95]
	v_pk_mul_f32 v[144:145], v[90:91], v[90:91]
	v_pk_mul_f32 v[146:147], v[94:95], v[94:95]
	s_waitcnt vmcnt(20)
	v_lshlrev_b32_e32 v92, 16, v142
	v_and_b32_e32 v93, 0xffff0000, v142
	v_add_f32_e32 v0, v144, v145
	v_pk_add_f32 v[92:93], v[86:87], v[92:93]
	v_lshlrev_b32_e32 v86, 16, v143
	v_and_b32_e32 v87, 0xffff0000, v143
	v_add_f32_e32 v0, v146, v0
	v_pk_add_f32 v[88:89], v[88:89], v[86:87]
	v_pk_mul_f32 v[86:87], v[92:93], v[92:93]
	v_add_f32_e32 v0, v147, v0
	v_add_f32_e32 v0, v86, v0
	v_pk_mul_f32 v[142:143], v[88:89], v[88:89]
	v_add_f32_e32 v0, v87, v0
	v_add_f32_e32 v0, v142, v0
	v_add_f32_e32 v0, v143, v0
	ds_bpermute_b32 v86, v190, v0
	s_waitcnt lgkmcnt(0)
	v_add_f32_e32 v0, v0, v86
	ds_bpermute_b32 v86, v191, v0
	s_and_saveexec_b64 s[62:63], s[4:5]
	s_cbranch_execz .LBB0_695
	s_waitcnt lgkmcnt(0)
	v_add_f32_e32 v0, v0, v86
	ds_write_b32 v185, v0 offset:1024
.LBB0_695:
	s_or_b64 exec, exec, s[62:63]
	s_waitcnt vmcnt(19) lgkmcnt(0)
	v_lshlrev_b32_e32 v86, 16, v138
	v_and_b32_e32 v87, 0xffff0000, v138
	v_pk_add_f32 v[86:87], v[82:83], v[86:87]
	v_lshlrev_b32_e32 v82, 16, v139
	v_and_b32_e32 v83, 0xffff0000, v139
	v_pk_add_f32 v[84:85], v[84:85], v[82:83]
	v_pk_mul_f32 v[138:139], v[86:87], v[86:87]
	v_pk_mul_f32 v[142:143], v[84:85], v[84:85]
	s_waitcnt vmcnt(18)
	v_lshlrev_b32_e32 v82, 16, v136
	v_and_b32_e32 v83, 0xffff0000, v136
	v_add_f32_e32 v0, v138, v139
	v_pk_add_f32 v[82:83], v[78:79], v[82:83]
	v_lshlrev_b32_e32 v78, 16, v137
	v_and_b32_e32 v79, 0xffff0000, v137
	v_add_f32_e32 v0, v142, v0
	v_pk_add_f32 v[78:79], v[80:81], v[78:79]
	v_pk_mul_f32 v[80:81], v[82:83], v[82:83]
	v_add_f32_e32 v0, v143, v0
	v_add_f32_e32 v0, v80, v0
	v_pk_mul_f32 v[136:137], v[78:79], v[78:79]
	v_add_f32_e32 v0, v81, v0
	v_add_f32_e32 v0, v136, v0
	v_add_f32_e32 v0, v137, v0
	ds_bpermute_b32 v80, v190, v0
	s_waitcnt lgkmcnt(0)
	v_add_f32_e32 v0, v0, v80
	ds_bpermute_b32 v80, v191, v0
	s_and_saveexec_b64 s[62:63], s[4:5]
	s_cbranch_execz .LBB0_679
	s_waitcnt lgkmcnt(0)
	v_add_f32_e32 v0, v0, v80
	ds_write_b32 v185, v0 offset:1536
	s_branch .LBB0_679
